# GU tile loop: redundant s_barrier after the final k-step removed (SwiGLU epilogue is LDS-free; the loop-control barrier already orders the next tile's LDS-DMA)
# baseline (speedup 1.0000x reference)
.Lg16_gu_k:
	s_add_i32 s8, s1, 2
	s_lshl_b32 s96, s8, 13
	s_add_i32 m0, vcc_lo, 16384
	v_lshl_add_u64 v[160:161], v[188:189], 0, s[96:97]
	global_load_lds_dwordx4 v[160:161], off
	global_load_lds_dwordx4 v[160:161], off offset:1024
	ds_read_b128 v[196:199], v246 offset:0
	ds_read_b128 v[200:203], v162 offset:0
	ds_read_b128 v[204:207], v246 offset:2048
	ds_read_b128 v[242:245], v162 offset:2048
	s_add_i32 s8, s1, 2
	s_lshl_b32 s96, s8, 11
	v_lshl_add_u64 v[248:249], v[184:185], 0, s[96:97]
	v_lshl_add_u64 v[250:251], v[186:187], 0, s[96:97]
	s_waitcnt vmcnt(8) lgkmcnt(3)
	v_mfma_f32_16x16x32_bf16 v[112:115], v[196:199], v[128:131], v[112:115]
	v_mfma_f32_16x16x32_bf16 v[120:123], v[196:199], v[132:135], v[120:123]
	v_mfma_f32_16x16x32_bf16 v[80:83], v[196:199], v[136:139], v[80:83]
	v_mfma_f32_16x16x32_bf16 v[88:91], v[196:199], v[140:143], v[88:91]
	ds_read_b128 v[196:199], v246 offset:4096
	s_waitcnt lgkmcnt(3)
	v_mfma_f32_16x16x32_bf16 v[116:119], v[200:203], v[128:131], v[116:119]
	v_mfma_f32_16x16x32_bf16 v[124:127], v[200:203], v[132:135], v[124:127]
	v_mfma_f32_16x16x32_bf16 v[84:87], v[200:203], v[136:139], v[84:87]
	v_mfma_f32_16x16x32_bf16 v[92:95], v[200:203], v[140:143], v[92:95]
	ds_read_b128 v[200:203], v162 offset:4096
	s_waitcnt lgkmcnt(3)
	v_mfma_f32_16x16x32_bf16 v[96:99], v[204:207], v[128:131], v[96:99]
	v_mfma_f32_16x16x32_bf16 v[104:107], v[204:207], v[132:135], v[104:107]
	v_mfma_f32_16x16x32_bf16 v[64:67], v[204:207], v[136:139], v[64:67]
	v_mfma_f32_16x16x32_bf16 v[72:75], v[204:207], v[140:143], v[72:75]
	ds_read_b128 v[204:207], v246 offset:6144
	s_waitcnt lgkmcnt(3)
	v_mfma_f32_16x16x32_bf16 v[100:103], v[242:245], v[128:131], v[100:103]
	v_mfma_f32_16x16x32_bf16 v[108:111], v[242:245], v[132:135], v[108:111]
	v_mfma_f32_16x16x32_bf16 v[68:71], v[242:245], v[136:139], v[68:71]
	v_mfma_f32_16x16x32_bf16 v[76:79], v[242:245], v[140:143], v[76:79]
	ds_read_b128 v[242:245], v162 offset:6144
	s_waitcnt lgkmcnt(3)
	v_mfma_f32_16x16x32_bf16 v[48:51], v[196:199], v[128:131], v[48:51]
	v_mfma_f32_16x16x32_bf16 v[56:59], v[196:199], v[132:135], v[56:59]
	v_mfma_f32_16x16x32_bf16 v[16:19], v[196:199], v[136:139], v[16:19]
	v_mfma_f32_16x16x32_bf16 v[24:27], v[196:199], v[140:143], v[24:27]
	s_waitcnt lgkmcnt(2)
	v_mfma_f32_16x16x32_bf16 v[52:55], v[200:203], v[128:131], v[52:55]
	v_mfma_f32_16x16x32_bf16 v[60:63], v[200:203], v[132:135], v[60:63]
	v_mfma_f32_16x16x32_bf16 v[20:23], v[200:203], v[136:139], v[20:23]
	v_mfma_f32_16x16x32_bf16 v[28:31], v[200:203], v[140:143], v[28:31]
	s_waitcnt lgkmcnt(1)
	v_mfma_f32_16x16x32_bf16 v[32:35], v[204:207], v[128:131], v[32:35]
	v_mfma_f32_16x16x32_bf16 v[40:43], v[204:207], v[132:135], v[40:43]
	v_mfma_f32_16x16x32_bf16 v[0:3], v[204:207], v[136:139], v[0:3]
	v_mfma_f32_16x16x32_bf16 v[8:11], v[204:207], v[140:143], v[8:11]
	s_waitcnt lgkmcnt(0)
	v_mfma_f32_16x16x32_bf16 v[36:39], v[242:245], v[128:131], v[36:39]
	v_mfma_f32_16x16x32_bf16 v[44:47], v[242:245], v[132:135], v[44:47]
	v_mfma_f32_16x16x32_bf16 v[4:7], v[242:245], v[136:139], v[4:7]
	v_mfma_f32_16x16x32_bf16 v[12:15], v[242:245], v[140:143], v[12:15]
	global_load_dwordx4 v[128:131], v[248:249], off
	global_load_dwordx4 v[132:135], v[248:249], off offset:256
	global_load_dwordx4 v[136:139], v[250:251], off
	global_load_dwordx4 v[140:143], v[250:251], off offset:256
	s_waitcnt vmcnt(10)
	s_barrier
	s_add_i32 s8, s1, 3
	s_lshl_b32 s96, s8, 13
	s_mov_b32 m0, vcc_lo
	v_lshl_add_u64 v[160:161], v[188:189], 0, s[96:97]
	global_load_lds_dwordx4 v[160:161], off
	global_load_lds_dwordx4 v[160:161], off offset:1024
	ds_read_b128 v[196:199], v246 offset:8192
	ds_read_b128 v[200:203], v162 offset:8192
	ds_read_b128 v[204:207], v246 offset:10240
	ds_read_b128 v[242:245], v162 offset:10240
	s_add_i32 s8, s1, 3
	s_lshl_b32 s96, s8, 11
	v_lshl_add_u64 v[248:249], v[184:185], 0, s[96:97]
	v_lshl_add_u64 v[250:251], v[186:187], 0, s[96:97]
	s_waitcnt vmcnt(8) lgkmcnt(3)
	v_mfma_f32_16x16x32_bf16 v[112:115], v[196:199], v[144:147], v[112:115]
	v_mfma_f32_16x16x32_bf16 v[120:123], v[196:199], v[148:151], v[120:123]
	v_mfma_f32_16x16x32_bf16 v[80:83], v[196:199], v[152:155], v[80:83]
	v_mfma_f32_16x16x32_bf16 v[88:91], v[196:199], v[156:159], v[88:91]
	ds_read_b128 v[196:199], v246 offset:12288
	s_waitcnt lgkmcnt(3)
	v_mfma_f32_16x16x32_bf16 v[116:119], v[200:203], v[144:147], v[116:119]
	v_mfma_f32_16x16x32_bf16 v[124:127], v[200:203], v[148:151], v[124:127]
	v_mfma_f32_16x16x32_bf16 v[84:87], v[200:203], v[152:155], v[84:87]
	v_mfma_f32_16x16x32_bf16 v[92:95], v[200:203], v[156:159], v[92:95]
	ds_read_b128 v[200:203], v162 offset:12288
	s_waitcnt lgkmcnt(3)
	v_mfma_f32_16x16x32_bf16 v[96:99], v[204:207], v[144:147], v[96:99]
	v_mfma_f32_16x16x32_bf16 v[104:107], v[204:207], v[148:151], v[104:107]
	v_mfma_f32_16x16x32_bf16 v[64:67], v[204:207], v[152:155], v[64:67]
	v_mfma_f32_16x16x32_bf16 v[72:75], v[204:207], v[156:159], v[72:75]
	ds_read_b128 v[204:207], v246 offset:14336
	s_waitcnt lgkmcnt(3)
	v_mfma_f32_16x16x32_bf16 v[100:103], v[242:245], v[144:147], v[100:103]
	v_mfma_f32_16x16x32_bf16 v[108:111], v[242:245], v[148:151], v[108:111]
	v_mfma_f32_16x16x32_bf16 v[68:71], v[242:245], v[152:155], v[68:71]
	v_mfma_f32_16x16x32_bf16 v[76:79], v[242:245], v[156:159], v[76:79]
	ds_read_b128 v[242:245], v162 offset:14336
	s_waitcnt lgkmcnt(3)
	v_mfma_f32_16x16x32_bf16 v[48:51], v[196:199], v[144:147], v[48:51]
	v_mfma_f32_16x16x32_bf16 v[56:59], v[196:199], v[148:151], v[56:59]
	v_mfma_f32_16x16x32_bf16 v[16:19], v[196:199], v[152:155], v[16:19]
	v_mfma_f32_16x16x32_bf16 v[24:27], v[196:199], v[156:159], v[24:27]
	s_waitcnt lgkmcnt(2)
	v_mfma_f32_16x16x32_bf16 v[52:55], v[200:203], v[144:147], v[52:55]
	v_mfma_f32_16x16x32_bf16 v[60:63], v[200:203], v[148:151], v[60:63]
	v_mfma_f32_16x16x32_bf16 v[20:23], v[200:203], v[152:155], v[20:23]
	v_mfma_f32_16x16x32_bf16 v[28:31], v[200:203], v[156:159], v[28:31]
	s_waitcnt lgkmcnt(1)
	v_mfma_f32_16x16x32_bf16 v[32:35], v[204:207], v[144:147], v[32:35]
	v_mfma_f32_16x16x32_bf16 v[40:43], v[204:207], v[148:151], v[40:43]
	v_mfma_f32_16x16x32_bf16 v[0:3], v[204:207], v[152:155], v[0:3]
	v_mfma_f32_16x16x32_bf16 v[8:11], v[204:207], v[156:159], v[8:11]
	s_waitcnt lgkmcnt(0)
	v_mfma_f32_16x16x32_bf16 v[36:39], v[242:245], v[144:147], v[36:39]
	v_mfma_f32_16x16x32_bf16 v[44:47], v[242:245], v[148:151], v[44:47]
	v_mfma_f32_16x16x32_bf16 v[4:7], v[242:245], v[152:155], v[4:7]
	v_mfma_f32_16x16x32_bf16 v[12:15], v[242:245], v[156:159], v[12:15]
	global_load_dwordx4 v[144:147], v[248:249], off
	global_load_dwordx4 v[148:151], v[248:249], off offset:256
	global_load_dwordx4 v[152:155], v[250:251], off
	global_load_dwordx4 v[156:159], v[250:251], off offset:256
	s_waitcnt vmcnt(10)
	s_barrier
	s_add_i32 s8, s1, 4
	s_lshl_b32 s96, s8, 13
	s_add_i32 m0, vcc_lo, 8192
	v_lshl_add_u64 v[160:161], v[188:189], 0, s[96:97]
	global_load_lds_dwordx4 v[160:161], off
	global_load_lds_dwordx4 v[160:161], off offset:1024
	ds_read_b128 v[196:199], v246 offset:16384
	ds_read_b128 v[200:203], v162 offset:16384
	ds_read_b128 v[204:207], v246 offset:18432
	ds_read_b128 v[242:245], v162 offset:18432
	s_add_i32 s8, s1, 4
	s_lshl_b32 s96, s8, 11
	v_lshl_add_u64 v[248:249], v[184:185], 0, s[96:97]
	v_lshl_add_u64 v[250:251], v[186:187], 0, s[96:97]
	s_waitcnt vmcnt(8) lgkmcnt(3)
	v_mfma_f32_16x16x32_bf16 v[112:115], v[196:199], v[128:131], v[112:115]
	v_mfma_f32_16x16x32_bf16 v[120:123], v[196:199], v[132:135], v[120:123]
	v_mfma_f32_16x16x32_bf16 v[80:83], v[196:199], v[136:139], v[80:83]
	v_mfma_f32_16x16x32_bf16 v[88:91], v[196:199], v[140:143], v[88:91]
	ds_read_b128 v[196:199], v246 offset:20480
	s_waitcnt lgkmcnt(3)
	v_mfma_f32_16x16x32_bf16 v[116:119], v[200:203], v[128:131], v[116:119]
	v_mfma_f32_16x16x32_bf16 v[124:127], v[200:203], v[132:135], v[124:127]
	v_mfma_f32_16x16x32_bf16 v[84:87], v[200:203], v[136:139], v[84:87]
	v_mfma_f32_16x16x32_bf16 v[92:95], v[200:203], v[140:143], v[92:95]
	ds_read_b128 v[200:203], v162 offset:20480
	s_waitcnt lgkmcnt(3)
	v_mfma_f32_16x16x32_bf16 v[96:99], v[204:207], v[128:131], v[96:99]
	v_mfma_f32_16x16x32_bf16 v[104:107], v[204:207], v[132:135], v[104:107]
	v_mfma_f32_16x16x32_bf16 v[64:67], v[204:207], v[136:139], v[64:67]
	v_mfma_f32_16x16x32_bf16 v[72:75], v[204:207], v[140:143], v[72:75]
	ds_read_b128 v[204:207], v246 offset:22528
	s_waitcnt lgkmcnt(3)
	v_mfma_f32_16x16x32_bf16 v[100:103], v[242:245], v[128:131], v[100:103]
	v_mfma_f32_16x16x32_bf16 v[108:111], v[242:245], v[132:135], v[108:111]
	v_mfma_f32_16x16x32_bf16 v[68:71], v[242:245], v[136:139], v[68:71]
	v_mfma_f32_16x16x32_bf16 v[76:79], v[242:245], v[140:143], v[76:79]
	ds_read_b128 v[242:245], v162 offset:22528
	s_waitcnt lgkmcnt(3)
	v_mfma_f32_16x16x32_bf16 v[48:51], v[196:199], v[128:131], v[48:51]
	v_mfma_f32_16x16x32_bf16 v[56:59], v[196:199], v[132:135], v[56:59]
	v_mfma_f32_16x16x32_bf16 v[16:19], v[196:199], v[136:139], v[16:19]
	v_mfma_f32_16x16x32_bf16 v[24:27], v[196:199], v[140:143], v[24:27]
	s_waitcnt lgkmcnt(2)
	v_mfma_f32_16x16x32_bf16 v[52:55], v[200:203], v[128:131], v[52:55]
	v_mfma_f32_16x16x32_bf16 v[60:63], v[200:203], v[132:135], v[60:63]
	v_mfma_f32_16x16x32_bf16 v[20:23], v[200:203], v[136:139], v[20:23]
	v_mfma_f32_16x16x32_bf16 v[28:31], v[200:203], v[140:143], v[28:31]
	s_waitcnt lgkmcnt(1)
	v_mfma_f32_16x16x32_bf16 v[32:35], v[204:207], v[128:131], v[32:35]
	v_mfma_f32_16x16x32_bf16 v[40:43], v[204:207], v[132:135], v[40:43]
	v_mfma_f32_16x16x32_bf16 v[0:3], v[204:207], v[136:139], v[0:3]
	v_mfma_f32_16x16x32_bf16 v[8:11], v[204:207], v[140:143], v[8:11]
	s_waitcnt lgkmcnt(0)
	v_mfma_f32_16x16x32_bf16 v[36:39], v[242:245], v[128:131], v[36:39]
	v_mfma_f32_16x16x32_bf16 v[44:47], v[242:245], v[132:135], v[44:47]
	v_mfma_f32_16x16x32_bf16 v[4:7], v[242:245], v[136:139], v[4:7]
	v_mfma_f32_16x16x32_bf16 v[12:15], v[242:245], v[140:143], v[12:15]
	global_load_dwordx4 v[128:131], v[248:249], off
	global_load_dwordx4 v[132:135], v[248:249], off offset:256
	global_load_dwordx4 v[136:139], v[250:251], off
	global_load_dwordx4 v[140:143], v[250:251], off offset:256
	s_waitcnt vmcnt(10)
	s_barrier
	s_add_i32 s8, s1, 5
	s_lshl_b32 s96, s8, 13
	s_add_i32 m0, vcc_lo, 16384
	v_lshl_add_u64 v[160:161], v[188:189], 0, s[96:97]
	global_load_lds_dwordx4 v[160:161], off
	global_load_lds_dwordx4 v[160:161], off offset:1024
	ds_read_b128 v[196:199], v246 offset:0
	ds_read_b128 v[200:203], v162 offset:0
	ds_read_b128 v[204:207], v246 offset:2048
	ds_read_b128 v[242:245], v162 offset:2048
	s_add_i32 s8, s1, 5
	s_lshl_b32 s96, s8, 11
	v_lshl_add_u64 v[248:249], v[184:185], 0, s[96:97]
	v_lshl_add_u64 v[250:251], v[186:187], 0, s[96:97]
	s_waitcnt vmcnt(8) lgkmcnt(3)
	v_mfma_f32_16x16x32_bf16 v[112:115], v[196:199], v[144:147], v[112:115]
	v_mfma_f32_16x16x32_bf16 v[120:123], v[196:199], v[148:151], v[120:123]
	v_mfma_f32_16x16x32_bf16 v[80:83], v[196:199], v[152:155], v[80:83]
	v_mfma_f32_16x16x32_bf16 v[88:91], v[196:199], v[156:159], v[88:91]
	ds_read_b128 v[196:199], v246 offset:4096
	s_waitcnt lgkmcnt(3)
	v_mfma_f32_16x16x32_bf16 v[116:119], v[200:203], v[144:147], v[116:119]
	v_mfma_f32_16x16x32_bf16 v[124:127], v[200:203], v[148:151], v[124:127]
	v_mfma_f32_16x16x32_bf16 v[84:87], v[200:203], v[152:155], v[84:87]
	v_mfma_f32_16x16x32_bf16 v[92:95], v[200:203], v[156:159], v[92:95]
	ds_read_b128 v[200:203], v162 offset:4096
	s_waitcnt lgkmcnt(3)
	v_mfma_f32_16x16x32_bf16 v[96:99], v[204:207], v[144:147], v[96:99]
	v_mfma_f32_16x16x32_bf16 v[104:107], v[204:207], v[148:151], v[104:107]
	v_mfma_f32_16x16x32_bf16 v[64:67], v[204:207], v[152:155], v[64:67]
	v_mfma_f32_16x16x32_bf16 v[72:75], v[204:207], v[156:159], v[72:75]
	ds_read_b128 v[204:207], v246 offset:6144
	s_waitcnt lgkmcnt(3)
	v_mfma_f32_16x16x32_bf16 v[100:103], v[242:245], v[144:147], v[100:103]
	v_mfma_f32_16x16x32_bf16 v[108:111], v[242:245], v[148:151], v[108:111]
	v_mfma_f32_16x16x32_bf16 v[68:71], v[242:245], v[152:155], v[68:71]
	v_mfma_f32_16x16x32_bf16 v[76:79], v[242:245], v[156:159], v[76:79]
	ds_read_b128 v[242:245], v162 offset:6144
	s_waitcnt lgkmcnt(3)
	v_mfma_f32_16x16x32_bf16 v[48:51], v[196:199], v[144:147], v[48:51]
	v_mfma_f32_16x16x32_bf16 v[56:59], v[196:199], v[148:151], v[56:59]
	v_mfma_f32_16x16x32_bf16 v[16:19], v[196:199], v[152:155], v[16:19]
	v_mfma_f32_16x16x32_bf16 v[24:27], v[196:199], v[156:159], v[24:27]
	s_waitcnt lgkmcnt(2)
	v_mfma_f32_16x16x32_bf16 v[52:55], v[200:203], v[144:147], v[52:55]
	v_mfma_f32_16x16x32_bf16 v[60:63], v[200:203], v[148:151], v[60:63]
	v_mfma_f32_16x16x32_bf16 v[20:23], v[200:203], v[152:155], v[20:23]
	v_mfma_f32_16x16x32_bf16 v[28:31], v[200:203], v[156:159], v[28:31]
	s_waitcnt lgkmcnt(1)
	v_mfma_f32_16x16x32_bf16 v[32:35], v[204:207], v[144:147], v[32:35]
	v_mfma_f32_16x16x32_bf16 v[40:43], v[204:207], v[148:151], v[40:43]
	v_mfma_f32_16x16x32_bf16 v[0:3], v[204:207], v[152:155], v[0:3]
	v_mfma_f32_16x16x32_bf16 v[8:11], v[204:207], v[156:159], v[8:11]
	s_waitcnt lgkmcnt(0)
	v_mfma_f32_16x16x32_bf16 v[36:39], v[242:245], v[144:147], v[36:39]
	v_mfma_f32_16x16x32_bf16 v[44:47], v[242:245], v[148:151], v[44:47]
	v_mfma_f32_16x16x32_bf16 v[4:7], v[242:245], v[152:155], v[4:7]
	v_mfma_f32_16x16x32_bf16 v[12:15], v[242:245], v[156:159], v[12:15]
	global_load_dwordx4 v[144:147], v[248:249], off
	global_load_dwordx4 v[148:151], v[248:249], off offset:256
	global_load_dwordx4 v[152:155], v[250:251], off
	global_load_dwordx4 v[156:159], v[250:251], off offset:256
	s_waitcnt vmcnt(10)
	s_barrier
	s_add_i32 s8, s1, 6
	s_lshl_b32 s96, s8, 13
	s_mov_b32 m0, vcc_lo
	v_lshl_add_u64 v[160:161], v[188:189], 0, s[96:97]
	global_load_lds_dwordx4 v[160:161], off
	global_load_lds_dwordx4 v[160:161], off offset:1024
	ds_read_b128 v[196:199], v246 offset:8192
	ds_read_b128 v[200:203], v162 offset:8192
	ds_read_b128 v[204:207], v246 offset:10240
	ds_read_b128 v[242:245], v162 offset:10240
	s_add_i32 s8, s1, 6
	s_lshl_b32 s96, s8, 11
	v_lshl_add_u64 v[248:249], v[184:185], 0, s[96:97]
	v_lshl_add_u64 v[250:251], v[186:187], 0, s[96:97]
	s_waitcnt vmcnt(8) lgkmcnt(3)
	v_mfma_f32_16x16x32_bf16 v[112:115], v[196:199], v[128:131], v[112:115]
	v_mfma_f32_16x16x32_bf16 v[120:123], v[196:199], v[132:135], v[120:123]
	v_mfma_f32_16x16x32_bf16 v[80:83], v[196:199], v[136:139], v[80:83]
	v_mfma_f32_16x16x32_bf16 v[88:91], v[196:199], v[140:143], v[88:91]
	ds_read_b128 v[196:199], v246 offset:12288
	s_waitcnt lgkmcnt(3)
	v_mfma_f32_16x16x32_bf16 v[116:119], v[200:203], v[128:131], v[116:119]
	v_mfma_f32_16x16x32_bf16 v[124:127], v[200:203], v[132:135], v[124:127]
	v_mfma_f32_16x16x32_bf16 v[84:87], v[200:203], v[136:139], v[84:87]
	v_mfma_f32_16x16x32_bf16 v[92:95], v[200:203], v[140:143], v[92:95]
	ds_read_b128 v[200:203], v162 offset:12288
	s_waitcnt lgkmcnt(3)
	v_mfma_f32_16x16x32_bf16 v[96:99], v[204:207], v[128:131], v[96:99]
	v_mfma_f32_16x16x32_bf16 v[104:107], v[204:207], v[132:135], v[104:107]
	v_mfma_f32_16x16x32_bf16 v[64:67], v[204:207], v[136:139], v[64:67]
	v_mfma_f32_16x16x32_bf16 v[72:75], v[204:207], v[140:143], v[72:75]
	ds_read_b128 v[204:207], v246 offset:14336
	s_waitcnt lgkmcnt(3)
	v_mfma_f32_16x16x32_bf16 v[100:103], v[242:245], v[128:131], v[100:103]
	v_mfma_f32_16x16x32_bf16 v[108:111], v[242:245], v[132:135], v[108:111]
	v_mfma_f32_16x16x32_bf16 v[68:71], v[242:245], v[136:139], v[68:71]
	v_mfma_f32_16x16x32_bf16 v[76:79], v[242:245], v[140:143], v[76:79]
	ds_read_b128 v[242:245], v162 offset:14336
	s_waitcnt lgkmcnt(3)
	v_mfma_f32_16x16x32_bf16 v[48:51], v[196:199], v[128:131], v[48:51]
	v_mfma_f32_16x16x32_bf16 v[56:59], v[196:199], v[132:135], v[56:59]
	v_mfma_f32_16x16x32_bf16 v[16:19], v[196:199], v[136:139], v[16:19]
	v_mfma_f32_16x16x32_bf16 v[24:27], v[196:199], v[140:143], v[24:27]
	s_waitcnt lgkmcnt(2)
	v_mfma_f32_16x16x32_bf16 v[52:55], v[200:203], v[128:131], v[52:55]
	v_mfma_f32_16x16x32_bf16 v[60:63], v[200:203], v[132:135], v[60:63]
	v_mfma_f32_16x16x32_bf16 v[20:23], v[200:203], v[136:139], v[20:23]
	v_mfma_f32_16x16x32_bf16 v[28:31], v[200:203], v[140:143], v[28:31]
	s_waitcnt lgkmcnt(1)
	v_mfma_f32_16x16x32_bf16 v[32:35], v[204:207], v[128:131], v[32:35]
	v_mfma_f32_16x16x32_bf16 v[40:43], v[204:207], v[132:135], v[40:43]
	v_mfma_f32_16x16x32_bf16 v[0:3], v[204:207], v[136:139], v[0:3]
	v_mfma_f32_16x16x32_bf16 v[8:11], v[204:207], v[140:143], v[8:11]
	s_waitcnt lgkmcnt(0)
	v_mfma_f32_16x16x32_bf16 v[36:39], v[242:245], v[128:131], v[36:39]
	v_mfma_f32_16x16x32_bf16 v[44:47], v[242:245], v[132:135], v[44:47]
	v_mfma_f32_16x16x32_bf16 v[4:7], v[242:245], v[136:139], v[4:7]
	v_mfma_f32_16x16x32_bf16 v[12:15], v[242:245], v[140:143], v[12:15]
	global_load_dwordx4 v[128:131], v[248:249], off
	global_load_dwordx4 v[132:135], v[248:249], off offset:256
	global_load_dwordx4 v[136:139], v[250:251], off
	global_load_dwordx4 v[140:143], v[250:251], off offset:256
	s_waitcnt vmcnt(10)
	s_barrier
	s_add_i32 s8, s1, 7
	s_lshl_b32 s96, s8, 13
	s_add_i32 m0, vcc_lo, 8192
	v_lshl_add_u64 v[160:161], v[188:189], 0, s[96:97]
	global_load_lds_dwordx4 v[160:161], off
	global_load_lds_dwordx4 v[160:161], off offset:1024
	ds_read_b128 v[196:199], v246 offset:16384
	ds_read_b128 v[200:203], v162 offset:16384
	ds_read_b128 v[204:207], v246 offset:18432
	ds_read_b128 v[242:245], v162 offset:18432
	s_add_i32 s8, s1, 7
	s_lshl_b32 s96, s8, 11
	v_lshl_add_u64 v[248:249], v[184:185], 0, s[96:97]
	v_lshl_add_u64 v[250:251], v[186:187], 0, s[96:97]
	s_waitcnt vmcnt(8) lgkmcnt(3)
	v_mfma_f32_16x16x32_bf16 v[112:115], v[196:199], v[144:147], v[112:115]
	v_mfma_f32_16x16x32_bf16 v[120:123], v[196:199], v[148:151], v[120:123]
	v_mfma_f32_16x16x32_bf16 v[80:83], v[196:199], v[152:155], v[80:83]
	v_mfma_f32_16x16x32_bf16 v[88:91], v[196:199], v[156:159], v[88:91]
	ds_read_b128 v[196:199], v246 offset:20480
	s_waitcnt lgkmcnt(3)
	v_mfma_f32_16x16x32_bf16 v[116:119], v[200:203], v[144:147], v[116:119]
	v_mfma_f32_16x16x32_bf16 v[124:127], v[200:203], v[148:151], v[124:127]
	v_mfma_f32_16x16x32_bf16 v[84:87], v[200:203], v[152:155], v[84:87]
	v_mfma_f32_16x16x32_bf16 v[92:95], v[200:203], v[156:159], v[92:95]
	ds_read_b128 v[200:203], v162 offset:20480
	s_waitcnt lgkmcnt(3)
	v_mfma_f32_16x16x32_bf16 v[96:99], v[204:207], v[144:147], v[96:99]
	v_mfma_f32_16x16x32_bf16 v[104:107], v[204:207], v[148:151], v[104:107]
	v_mfma_f32_16x16x32_bf16 v[64:67], v[204:207], v[152:155], v[64:67]
	v_mfma_f32_16x16x32_bf16 v[72:75], v[204:207], v[156:159], v[72:75]
	ds_read_b128 v[204:207], v246 offset:22528
	s_waitcnt lgkmcnt(3)
	v_mfma_f32_16x16x32_bf16 v[100:103], v[242:245], v[144:147], v[100:103]
	v_mfma_f32_16x16x32_bf16 v[108:111], v[242:245], v[148:151], v[108:111]
	v_mfma_f32_16x16x32_bf16 v[68:71], v[242:245], v[152:155], v[68:71]
	v_mfma_f32_16x16x32_bf16 v[76:79], v[242:245], v[156:159], v[76:79]
	ds_read_b128 v[242:245], v162 offset:22528
	s_waitcnt lgkmcnt(3)
	v_mfma_f32_16x16x32_bf16 v[48:51], v[196:199], v[144:147], v[48:51]
	v_mfma_f32_16x16x32_bf16 v[56:59], v[196:199], v[148:151], v[56:59]
	v_mfma_f32_16x16x32_bf16 v[16:19], v[196:199], v[152:155], v[16:19]
	v_mfma_f32_16x16x32_bf16 v[24:27], v[196:199], v[156:159], v[24:27]
	s_waitcnt lgkmcnt(2)
	v_mfma_f32_16x16x32_bf16 v[52:55], v[200:203], v[144:147], v[52:55]
	v_mfma_f32_16x16x32_bf16 v[60:63], v[200:203], v[148:151], v[60:63]
	v_mfma_f32_16x16x32_bf16 v[20:23], v[200:203], v[152:155], v[20:23]
	v_mfma_f32_16x16x32_bf16 v[28:31], v[200:203], v[156:159], v[28:31]
	s_waitcnt lgkmcnt(1)
	v_mfma_f32_16x16x32_bf16 v[32:35], v[204:207], v[144:147], v[32:35]
	v_mfma_f32_16x16x32_bf16 v[40:43], v[204:207], v[148:151], v[40:43]
	v_mfma_f32_16x16x32_bf16 v[0:3], v[204:207], v[152:155], v[0:3]
	v_mfma_f32_16x16x32_bf16 v[8:11], v[204:207], v[156:159], v[8:11]
	s_waitcnt lgkmcnt(0)
	v_mfma_f32_16x16x32_bf16 v[36:39], v[242:245], v[144:147], v[36:39]
	v_mfma_f32_16x16x32_bf16 v[44:47], v[242:245], v[148:151], v[44:47]
	v_mfma_f32_16x16x32_bf16 v[4:7], v[242:245], v[152:155], v[4:7]
	v_mfma_f32_16x16x32_bf16 v[12:15], v[242:245], v[156:159], v[12:15]
	global_load_dwordx4 v[144:147], v[248:249], off
	global_load_dwordx4 v[148:151], v[248:249], off offset:256
	global_load_dwordx4 v[152:155], v[250:251], off
	global_load_dwordx4 v[156:159], v[250:251], off offset:256
	s_waitcnt vmcnt(10)
	s_barrier
	s_add_i32 s1, s1, 6
	s_cmp_lt_u32 s1, 30
	s_cbranch_scc1 .Lg16_gu_k
	ds_read_b128 v[196:199], v246 offset:0
	ds_read_b128 v[200:203], v162 offset:0
	ds_read_b128 v[204:207], v246 offset:2048
	ds_read_b128 v[242:245], v162 offset:2048
	s_waitcnt vmcnt(6) lgkmcnt(3)
	v_mfma_f32_16x16x32_bf16 v[112:115], v[196:199], v[128:131], v[112:115]
	v_mfma_f32_16x16x32_bf16 v[120:123], v[196:199], v[132:135], v[120:123]
	v_mfma_f32_16x16x32_bf16 v[80:83], v[196:199], v[136:139], v[80:83]
	v_mfma_f32_16x16x32_bf16 v[88:91], v[196:199], v[140:143], v[88:91]
	ds_read_b128 v[196:199], v246 offset:4096
	s_waitcnt lgkmcnt(3)
	v_mfma_f32_16x16x32_bf16 v[116:119], v[200:203], v[128:131], v[116:119]
	v_mfma_f32_16x16x32_bf16 v[124:127], v[200:203], v[132:135], v[124:127]
	v_mfma_f32_16x16x32_bf16 v[84:87], v[200:203], v[136:139], v[84:87]
	v_mfma_f32_16x16x32_bf16 v[92:95], v[200:203], v[140:143], v[92:95]
	ds_read_b128 v[200:203], v162 offset:4096
	s_waitcnt lgkmcnt(3)
	v_mfma_f32_16x16x32_bf16 v[96:99], v[204:207], v[128:131], v[96:99]
	v_mfma_f32_16x16x32_bf16 v[104:107], v[204:207], v[132:135], v[104:107]
	v_mfma_f32_16x16x32_bf16 v[64:67], v[204:207], v[136:139], v[64:67]
	v_mfma_f32_16x16x32_bf16 v[72:75], v[204:207], v[140:143], v[72:75]
	ds_read_b128 v[204:207], v246 offset:6144
	s_waitcnt lgkmcnt(3)
	v_mfma_f32_16x16x32_bf16 v[100:103], v[242:245], v[128:131], v[100:103]
	v_mfma_f32_16x16x32_bf16 v[108:111], v[242:245], v[132:135], v[108:111]
	v_mfma_f32_16x16x32_bf16 v[68:71], v[242:245], v[136:139], v[68:71]
	v_mfma_f32_16x16x32_bf16 v[76:79], v[242:245], v[140:143], v[76:79]
	ds_read_b128 v[242:245], v162 offset:6144
	s_waitcnt lgkmcnt(3)
	v_mfma_f32_16x16x32_bf16 v[48:51], v[196:199], v[128:131], v[48:51]
	v_mfma_f32_16x16x32_bf16 v[56:59], v[196:199], v[132:135], v[56:59]
	v_mfma_f32_16x16x32_bf16 v[16:19], v[196:199], v[136:139], v[16:19]
	v_mfma_f32_16x16x32_bf16 v[24:27], v[196:199], v[140:143], v[24:27]
	s_waitcnt lgkmcnt(2)
	v_mfma_f32_16x16x32_bf16 v[52:55], v[200:203], v[128:131], v[52:55]
	v_mfma_f32_16x16x32_bf16 v[60:63], v[200:203], v[132:135], v[60:63]
	v_mfma_f32_16x16x32_bf16 v[20:23], v[200:203], v[136:139], v[20:23]
	v_mfma_f32_16x16x32_bf16 v[28:31], v[200:203], v[140:143], v[28:31]
	s_waitcnt lgkmcnt(1)
	v_mfma_f32_16x16x32_bf16 v[32:35], v[204:207], v[128:131], v[32:35]
	v_mfma_f32_16x16x32_bf16 v[40:43], v[204:207], v[132:135], v[40:43]
	v_mfma_f32_16x16x32_bf16 v[0:3], v[204:207], v[136:139], v[0:3]
	v_mfma_f32_16x16x32_bf16 v[8:11], v[204:207], v[140:143], v[8:11]
	s_waitcnt lgkmcnt(0)
	v_mfma_f32_16x16x32_bf16 v[36:39], v[242:245], v[128:131], v[36:39]
	v_mfma_f32_16x16x32_bf16 v[44:47], v[242:245], v[132:135], v[44:47]
	v_mfma_f32_16x16x32_bf16 v[4:7], v[242:245], v[136:139], v[4:7]
	v_mfma_f32_16x16x32_bf16 v[12:15], v[242:245], v[140:143], v[12:15]
	s_waitcnt vmcnt(4)
	s_barrier
	ds_read_b128 v[196:199], v246 offset:8192
	ds_read_b128 v[200:203], v162 offset:8192
	ds_read_b128 v[204:207], v246 offset:10240
	ds_read_b128 v[242:245], v162 offset:10240
	s_waitcnt vmcnt(0) lgkmcnt(3)
	v_mfma_f32_16x16x32_bf16 v[112:115], v[196:199], v[144:147], v[112:115]
	v_mfma_f32_16x16x32_bf16 v[120:123], v[196:199], v[148:151], v[120:123]
	v_mfma_f32_16x16x32_bf16 v[80:83], v[196:199], v[152:155], v[80:83]
	v_mfma_f32_16x16x32_bf16 v[88:91], v[196:199], v[156:159], v[88:91]
	ds_read_b128 v[196:199], v246 offset:12288
	s_waitcnt lgkmcnt(3)
	v_mfma_f32_16x16x32_bf16 v[116:119], v[200:203], v[144:147], v[116:119]
	v_mfma_f32_16x16x32_bf16 v[124:127], v[200:203], v[148:151], v[124:127]
	v_mfma_f32_16x16x32_bf16 v[84:87], v[200:203], v[152:155], v[84:87]
	v_mfma_f32_16x16x32_bf16 v[92:95], v[200:203], v[156:159], v[92:95]
	ds_read_b128 v[200:203], v162 offset:12288
	s_waitcnt lgkmcnt(3)
	v_mfma_f32_16x16x32_bf16 v[96:99], v[204:207], v[144:147], v[96:99]
	v_mfma_f32_16x16x32_bf16 v[104:107], v[204:207], v[148:151], v[104:107]
	v_mfma_f32_16x16x32_bf16 v[64:67], v[204:207], v[152:155], v[64:67]
	v_mfma_f32_16x16x32_bf16 v[72:75], v[204:207], v[156:159], v[72:75]
	ds_read_b128 v[204:207], v246 offset:14336
	s_waitcnt lgkmcnt(3)
	v_mfma_f32_16x16x32_bf16 v[100:103], v[242:245], v[144:147], v[100:103]
	v_mfma_f32_16x16x32_bf16 v[108:111], v[242:245], v[148:151], v[108:111]
	v_mfma_f32_16x16x32_bf16 v[68:71], v[242:245], v[152:155], v[68:71]
	v_mfma_f32_16x16x32_bf16 v[76:79], v[242:245], v[156:159], v[76:79]
	ds_read_b128 v[242:245], v162 offset:14336
	s_waitcnt lgkmcnt(3)
	v_mfma_f32_16x16x32_bf16 v[48:51], v[196:199], v[144:147], v[48:51]
	v_mfma_f32_16x16x32_bf16 v[56:59], v[196:199], v[148:151], v[56:59]
	v_mfma_f32_16x16x32_bf16 v[16:19], v[196:199], v[152:155], v[16:19]
	v_mfma_f32_16x16x32_bf16 v[24:27], v[196:199], v[156:159], v[24:27]
	s_waitcnt lgkmcnt(2)
	v_mfma_f32_16x16x32_bf16 v[52:55], v[200:203], v[144:147], v[52:55]
	v_mfma_f32_16x16x32_bf16 v[60:63], v[200:203], v[148:151], v[60:63]
	v_mfma_f32_16x16x32_bf16 v[20:23], v[200:203], v[152:155], v[20:23]
	v_mfma_f32_16x16x32_bf16 v[28:31], v[200:203], v[156:159], v[28:31]
	s_waitcnt lgkmcnt(1)
	v_mfma_f32_16x16x32_bf16 v[32:35], v[204:207], v[144:147], v[32:35]
	v_mfma_f32_16x16x32_bf16 v[40:43], v[204:207], v[148:151], v[40:43]
	v_mfma_f32_16x16x32_bf16 v[0:3], v[204:207], v[152:155], v[0:3]
	v_mfma_f32_16x16x32_bf16 v[8:11], v[204:207], v[156:159], v[8:11]
	s_waitcnt lgkmcnt(0)
	v_mfma_f32_16x16x32_bf16 v[36:39], v[242:245], v[144:147], v[36:39]
	v_mfma_f32_16x16x32_bf16 v[44:47], v[242:245], v[148:151], v[44:47]
	v_mfma_f32_16x16x32_bf16 v[4:7], v[242:245], v[152:155], v[4:7]
	v_mfma_f32_16x16x32_bf16 v[12:15], v[242:245], v[156:159], v[12:15]
	s_nop 7
	s_nop 1
	s_waitcnt vmcnt(0)
	v_and_b32_e32 v128, 63, v179
	v_lshrrev_b32_e32 v129, 6, v179
	s_lshl_b32 s14, s7, 3
	s_mul_hi_u32 s15, s14, 0x2c000
	s_mul_i32 s14, s14, 0x2c000
	s_lshl_b32 s16, s0, 12
	s_add_u32 s12, s66, s14
	s_addc_u32 s13, s67, s15
	s_add_u32 s12, s12, s16
	s_addc_u32 s13, s13, 0
	v_and_b32_e32 v130, 15, v128
	v_lshlrev_b32_e32 v132, 4, v130
	v_lshrrev_b32_e32 v130, 4, v128
	v_lshl_add_u32 v132, v130, 9, v132
	v_mul_u32_u24_e32 v130, 0x58000, v129
	v_add_u32_e32 v132, v132, v130
	v_add_u32_e32 v133, 0x2c000, v132
	v_mul_f32_e32 v140, 0xbfb8aa3b, v112
	v_mul_f32_e32 v141, 0xbfb8aa3b, v113
	v_mul_f32_e32 v142, 0xbfb8aa3b, v114
	v_mul_f32_e32 v143, 0xbfb8aa3b, v115
	v_mul_f32_e32 v144, 0xbfb8aa3b, v116
	v_mul_f32_e32 v145, 0xbfb8aa3b, v117
	v_mul_f32_e32 v146, 0xbfb8aa3b, v118
	v_mul_f32_e32 v147, 0xbfb8aa3b, v119
	v_exp_f32_e32 v140, v140
	v_exp_f32_e32 v141, v141
	v_exp_f32_e32 v142, v142
	v_exp_f32_e32 v143, v143
	v_exp_f32_e32 v144, v144
	v_exp_f32_e32 v145, v145
	v_exp_f32_e32 v146, v146
	v_exp_f32_e32 v147, v147
	v_add_f32_e32 v140, 1.0, v140
	v_add_f32_e32 v141, 1.0, v141
	v_add_f32_e32 v142, 1.0, v142
	v_add_f32_e32 v143, 1.0, v143
	v_add_f32_e32 v144, 1.0, v144
	v_add_f32_e32 v145, 1.0, v145
	v_add_f32_e32 v146, 1.0, v146
	v_add_f32_e32 v147, 1.0, v147
	v_rcp_f32_e32 v140, v140
	v_rcp_f32_e32 v141, v141
	v_rcp_f32_e32 v142, v142
	v_rcp_f32_e32 v143, v143
	v_rcp_f32_e32 v144, v144
	v_rcp_f32_e32 v145, v145
	v_rcp_f32_e32 v146, v146
	v_rcp_f32_e32 v147, v147
	v_mul_f32_e32 v140, v112, v140
	v_mul_f32_e32 v141, v113, v141
	v_mul_f32_e32 v142, v114, v142
	v_mul_f32_e32 v143, v115, v143
	v_mul_f32_e32 v144, v116, v144
	v_mul_f32_e32 v145, v117, v145
	v_mul_f32_e32 v146, v118, v146
	v_mul_f32_e32 v147, v119, v147
	v_mul_f32_e32 v140, v96, v140
	v_mul_f32_e32 v141, v97, v141
	v_mul_f32_e32 v142, v98, v142
	v_mul_f32_e32 v143, v99, v143
	v_mul_f32_e32 v144, v100, v144
	v_mul_f32_e32 v145, v101, v145
	v_mul_f32_e32 v146, v102, v146
	v_mul_f32_e32 v147, v103, v147
	v_cvt_pk_bf16_f32 v148, v140, v141
	v_cvt_pk_bf16_f32 v149, v142, v143
	v_cvt_pk_bf16_f32 v150, v144, v145
	v_cvt_pk_bf16_f32 v151, v146, v147
	global_store_dwordx4 v132, v[148:151], s[12:13] sc0 sc1
	v_mul_f32_e32 v140, 0xbfb8aa3b, v120
	v_mul_f32_e32 v141, 0xbfb8aa3b, v121
	v_mul_f32_e32 v142, 0xbfb8aa3b, v122
	v_mul_f32_e32 v143, 0xbfb8aa3b, v123
	v_mul_f32_e32 v144, 0xbfb8aa3b, v124
	v_mul_f32_e32 v145, 0xbfb8aa3b, v125
	v_mul_f32_e32 v146, 0xbfb8aa3b, v126
	v_mul_f32_e32 v147, 0xbfb8aa3b, v127
	v_exp_f32_e32 v140, v140
	v_exp_f32_e32 v141, v141
	v_exp_f32_e32 v142, v142
	v_exp_f32_e32 v143, v143
	v_exp_f32_e32 v144, v144
	v_exp_f32_e32 v145, v145
	v_exp_f32_e32 v146, v146
	v_exp_f32_e32 v147, v147
	v_add_f32_e32 v140, 1.0, v140
	v_add_f32_e32 v141, 1.0, v141
	v_add_f32_e32 v142, 1.0, v142
	v_add_f32_e32 v143, 1.0, v143
	v_add_f32_e32 v144, 1.0, v144
	v_add_f32_e32 v145, 1.0, v145
	v_add_f32_e32 v146, 1.0, v146
	v_add_f32_e32 v147, 1.0, v147
	v_rcp_f32_e32 v140, v140
	v_rcp_f32_e32 v141, v141
	v_rcp_f32_e32 v142, v142
	v_rcp_f32_e32 v143, v143
	v_rcp_f32_e32 v144, v144
	v_rcp_f32_e32 v145, v145
	v_rcp_f32_e32 v146, v146
	v_rcp_f32_e32 v147, v147
	v_mul_f32_e32 v140, v120, v140
	v_mul_f32_e32 v141, v121, v141
	v_mul_f32_e32 v142, v122, v142
	v_mul_f32_e32 v143, v123, v143
	v_mul_f32_e32 v144, v124, v144
	v_mul_f32_e32 v145, v125, v145
	v_mul_f32_e32 v146, v126, v146
	v_mul_f32_e32 v147, v127, v147
	v_mul_f32_e32 v140, v104, v140
	v_mul_f32_e32 v141, v105, v141
	v_mul_f32_e32 v142, v106, v142
	v_mul_f32_e32 v143, v107, v143
	v_mul_f32_e32 v144, v108, v144
	v_mul_f32_e32 v145, v109, v145
	v_mul_f32_e32 v146, v110, v146
	v_mul_f32_e32 v147, v111, v147
	v_cvt_pk_bf16_f32 v152, v140, v141
	v_cvt_pk_bf16_f32 v153, v142, v143
	v_cvt_pk_bf16_f32 v154, v144, v145
	v_cvt_pk_bf16_f32 v155, v146, v147
	global_store_dwordx4 v132, v[152:155], s[12:13] offset:256 sc0 sc1
	v_mul_f32_e32 v140, 0xbfb8aa3b, v80
	v_mul_f32_e32 v141, 0xbfb8aa3b, v81
	v_mul_f32_e32 v142, 0xbfb8aa3b, v82
	v_mul_f32_e32 v143, 0xbfb8aa3b, v83
	v_mul_f32_e32 v144, 0xbfb8aa3b, v84
	v_mul_f32_e32 v145, 0xbfb8aa3b, v85
	v_mul_f32_e32 v146, 0xbfb8aa3b, v86
	v_mul_f32_e32 v147, 0xbfb8aa3b, v87
	v_exp_f32_e32 v140, v140
	v_exp_f32_e32 v141, v141
	v_exp_f32_e32 v142, v142
	v_exp_f32_e32 v143, v143
	v_exp_f32_e32 v144, v144
	v_exp_f32_e32 v145, v145
	v_exp_f32_e32 v146, v146
	v_exp_f32_e32 v147, v147
	v_add_f32_e32 v140, 1.0, v140
	v_add_f32_e32 v141, 1.0, v141
	v_add_f32_e32 v142, 1.0, v142
	v_add_f32_e32 v143, 1.0, v143
	v_add_f32_e32 v144, 1.0, v144
	v_add_f32_e32 v145, 1.0, v145
	v_add_f32_e32 v146, 1.0, v146
	v_add_f32_e32 v147, 1.0, v147
	v_rcp_f32_e32 v140, v140
	v_rcp_f32_e32 v141, v141
	v_rcp_f32_e32 v142, v142
	v_rcp_f32_e32 v143, v143
	v_rcp_f32_e32 v144, v144
	v_rcp_f32_e32 v145, v145
	v_rcp_f32_e32 v146, v146
	v_rcp_f32_e32 v147, v147
	v_mul_f32_e32 v140, v80, v140
	v_mul_f32_e32 v141, v81, v141
	v_mul_f32_e32 v142, v82, v142
	v_mul_f32_e32 v143, v83, v143
	v_mul_f32_e32 v144, v84, v144
	v_mul_f32_e32 v145, v85, v145
	v_mul_f32_e32 v146, v86, v146
	v_mul_f32_e32 v147, v87, v147
	v_mul_f32_e32 v140, v64, v140
	v_mul_f32_e32 v141, v65, v141
	v_mul_f32_e32 v142, v66, v142
	v_mul_f32_e32 v143, v67, v143
	v_mul_f32_e32 v144, v68, v144
	v_mul_f32_e32 v145, v69, v145
	v_mul_f32_e32 v146, v70, v146
	v_mul_f32_e32 v147, v71, v147
	v_cvt_pk_bf16_f32 v156, v140, v141
	v_cvt_pk_bf16_f32 v157, v142, v143
	v_cvt_pk_bf16_f32 v158, v144, v145
	v_cvt_pk_bf16_f32 v159, v146, v147
	global_store_dwordx4 v133, v[156:159], s[12:13] sc0 sc1
	v_mul_f32_e32 v140, 0xbfb8aa3b, v88
	v_mul_f32_e32 v141, 0xbfb8aa3b, v89
	v_mul_f32_e32 v142, 0xbfb8aa3b, v90
	v_mul_f32_e32 v143, 0xbfb8aa3b, v91
	v_mul_f32_e32 v144, 0xbfb8aa3b, v92
	v_mul_f32_e32 v145, 0xbfb8aa3b, v93
	v_mul_f32_e32 v146, 0xbfb8aa3b, v94
	v_mul_f32_e32 v147, 0xbfb8aa3b, v95
	v_exp_f32_e32 v140, v140
	v_exp_f32_e32 v141, v141
	v_exp_f32_e32 v142, v142
	v_exp_f32_e32 v143, v143
	v_exp_f32_e32 v144, v144
	v_exp_f32_e32 v145, v145
	v_exp_f32_e32 v146, v146
	v_exp_f32_e32 v147, v147
	v_add_f32_e32 v140, 1.0, v140
	v_add_f32_e32 v141, 1.0, v141
	v_add_f32_e32 v142, 1.0, v142
	v_add_f32_e32 v143, 1.0, v143
	v_add_f32_e32 v144, 1.0, v144
	v_add_f32_e32 v145, 1.0, v145
	v_add_f32_e32 v146, 1.0, v146
	v_add_f32_e32 v147, 1.0, v147
	v_rcp_f32_e32 v140, v140
	v_rcp_f32_e32 v141, v141
	v_rcp_f32_e32 v142, v142
	v_rcp_f32_e32 v143, v143
	v_rcp_f32_e32 v144, v144
	v_rcp_f32_e32 v145, v145
	v_rcp_f32_e32 v146, v146
	v_rcp_f32_e32 v147, v147
	v_mul_f32_e32 v140, v88, v140
	v_mul_f32_e32 v141, v89, v141
	v_mul_f32_e32 v142, v90, v142
	v_mul_f32_e32 v143, v91, v143
	v_mul_f32_e32 v144, v92, v144
	v_mul_f32_e32 v145, v93, v145
	v_mul_f32_e32 v146, v94, v146
	v_mul_f32_e32 v147, v95, v147
	v_mul_f32_e32 v140, v72, v140
	v_mul_f32_e32 v141, v73, v141
	v_mul_f32_e32 v142, v74, v142
	v_mul_f32_e32 v143, v75, v143
	v_mul_f32_e32 v144, v76, v144
	v_mul_f32_e32 v145, v77, v145
	v_mul_f32_e32 v146, v78, v146
	v_mul_f32_e32 v147, v79, v147
	v_cvt_pk_bf16_f32 v160, v140, v141
	v_cvt_pk_bf16_f32 v161, v142, v143
	v_cvt_pk_bf16_f32 v162, v144, v145
	v_cvt_pk_bf16_f32 v163, v146, v147
	global_store_dwordx4 v133, v[160:163], s[12:13] offset:256 sc0 sc1
	v_mul_f32_e32 v140, 0xbfb8aa3b, v48
	v_mul_f32_e32 v141, 0xbfb8aa3b, v49
	v_mul_f32_e32 v142, 0xbfb8aa3b, v50
	v_mul_f32_e32 v143, 0xbfb8aa3b, v51
	v_mul_f32_e32 v144, 0xbfb8aa3b, v52
	v_mul_f32_e32 v145, 0xbfb8aa3b, v53
	v_mul_f32_e32 v146, 0xbfb8aa3b, v54
	v_mul_f32_e32 v147, 0xbfb8aa3b, v55
	v_exp_f32_e32 v140, v140
	v_exp_f32_e32 v141, v141
	v_exp_f32_e32 v142, v142
	v_exp_f32_e32 v143, v143
	v_exp_f32_e32 v144, v144
	v_exp_f32_e32 v145, v145
	v_exp_f32_e32 v146, v146
	v_exp_f32_e32 v147, v147
	v_add_f32_e32 v140, 1.0, v140
	v_add_f32_e32 v141, 1.0, v141
	v_add_f32_e32 v142, 1.0, v142
	v_add_f32_e32 v143, 1.0, v143
	v_add_f32_e32 v144, 1.0, v144
	v_add_f32_e32 v145, 1.0, v145
	v_add_f32_e32 v146, 1.0, v146
	v_add_f32_e32 v147, 1.0, v147
	v_rcp_f32_e32 v140, v140
	v_rcp_f32_e32 v141, v141
	v_rcp_f32_e32 v142, v142
	v_rcp_f32_e32 v143, v143
	v_rcp_f32_e32 v144, v144
	v_rcp_f32_e32 v145, v145
	v_rcp_f32_e32 v146, v146
	v_rcp_f32_e32 v147, v147
	v_mul_f32_e32 v140, v48, v140
	v_mul_f32_e32 v141, v49, v141
	v_mul_f32_e32 v142, v50, v142
	v_mul_f32_e32 v143, v51, v143
	v_mul_f32_e32 v144, v52, v144
	v_mul_f32_e32 v145, v53, v145
	v_mul_f32_e32 v146, v54, v146
	v_mul_f32_e32 v147, v55, v147
	v_mul_f32_e32 v140, v32, v140
	v_mul_f32_e32 v141, v33, v141
	v_mul_f32_e32 v142, v34, v142
	v_mul_f32_e32 v143, v35, v143
	v_mul_f32_e32 v144, v36, v144
	v_mul_f32_e32 v145, v37, v145
	v_mul_f32_e32 v146, v38, v146
	v_mul_f32_e32 v147, v39, v147
	v_cvt_pk_bf16_f32 v148, v140, v141
	v_cvt_pk_bf16_f32 v149, v142, v143
	v_cvt_pk_bf16_f32 v150, v144, v145
	v_cvt_pk_bf16_f32 v151, v146, v147
	global_store_dwordx4 v132, v[148:151], s[12:13] offset:2048 sc0 sc1
	v_mul_f32_e32 v140, 0xbfb8aa3b, v56
	v_mul_f32_e32 v141, 0xbfb8aa3b, v57
	v_mul_f32_e32 v142, 0xbfb8aa3b, v58
	v_mul_f32_e32 v143, 0xbfb8aa3b, v59
	v_mul_f32_e32 v144, 0xbfb8aa3b, v60
	v_mul_f32_e32 v145, 0xbfb8aa3b, v61
	v_mul_f32_e32 v146, 0xbfb8aa3b, v62
	v_mul_f32_e32 v147, 0xbfb8aa3b, v63
	v_exp_f32_e32 v140, v140
	v_exp_f32_e32 v141, v141
	v_exp_f32_e32 v142, v142
	v_exp_f32_e32 v143, v143
	v_exp_f32_e32 v144, v144
	v_exp_f32_e32 v145, v145
	v_exp_f32_e32 v146, v146
	v_exp_f32_e32 v147, v147
	v_add_f32_e32 v140, 1.0, v140
	v_add_f32_e32 v141, 1.0, v141
	v_add_f32_e32 v142, 1.0, v142
	v_add_f32_e32 v143, 1.0, v143
	v_add_f32_e32 v144, 1.0, v144
	v_add_f32_e32 v145, 1.0, v145
	v_add_f32_e32 v146, 1.0, v146
	v_add_f32_e32 v147, 1.0, v147
	v_rcp_f32_e32 v140, v140
	v_rcp_f32_e32 v141, v141
	v_rcp_f32_e32 v142, v142
	v_rcp_f32_e32 v143, v143
	v_rcp_f32_e32 v144, v144
	v_rcp_f32_e32 v145, v145
	v_rcp_f32_e32 v146, v146
	v_rcp_f32_e32 v147, v147
	v_mul_f32_e32 v140, v56, v140
	v_mul_f32_e32 v141, v57, v141
	v_mul_f32_e32 v142, v58, v142
	v_mul_f32_e32 v143, v59, v143
	v_mul_f32_e32 v144, v60, v144
	v_mul_f32_e32 v145, v61, v145
	v_mul_f32_e32 v146, v62, v146
	v_mul_f32_e32 v147, v63, v147
	v_mul_f32_e32 v140, v40, v140
	v_mul_f32_e32 v141, v41, v141
	v_mul_f32_e32 v142, v42, v142
	v_mul_f32_e32 v143, v43, v143
	v_mul_f32_e32 v144, v44, v144
	v_mul_f32_e32 v145, v45, v145
	v_mul_f32_e32 v146, v46, v146
	v_mul_f32_e32 v147, v47, v147
	v_cvt_pk_bf16_f32 v152, v140, v141
	v_cvt_pk_bf16_f32 v153, v142, v143
	v_cvt_pk_bf16_f32 v154, v144, v145
	v_cvt_pk_bf16_f32 v155, v146, v147
	global_store_dwordx4 v132, v[152:155], s[12:13] offset:2304 sc0 sc1
	v_mul_f32_e32 v140, 0xbfb8aa3b, v16
	v_mul_f32_e32 v141, 0xbfb8aa3b, v17
	v_mul_f32_e32 v142, 0xbfb8aa3b, v18
	v_mul_f32_e32 v143, 0xbfb8aa3b, v19
	v_mul_f32_e32 v144, 0xbfb8aa3b, v20
	v_mul_f32_e32 v145, 0xbfb8aa3b, v21
	v_mul_f32_e32 v146, 0xbfb8aa3b, v22
	v_mul_f32_e32 v147, 0xbfb8aa3b, v23
	v_exp_f32_e32 v140, v140
	v_exp_f32_e32 v141, v141
	v_exp_f32_e32 v142, v142
	v_exp_f32_e32 v143, v143
	v_exp_f32_e32 v144, v144
	v_exp_f32_e32 v145, v145
	v_exp_f32_e32 v146, v146
	v_exp_f32_e32 v147, v147
	v_add_f32_e32 v140, 1.0, v140
	v_add_f32_e32 v141, 1.0, v141
	v_add_f32_e32 v142, 1.0, v142
	v_add_f32_e32 v143, 1.0, v143
	v_add_f32_e32 v144, 1.0, v144
	v_add_f32_e32 v145, 1.0, v145
	v_add_f32_e32 v146, 1.0, v146
	v_add_f32_e32 v147, 1.0, v147
	v_rcp_f32_e32 v140, v140
	v_rcp_f32_e32 v141, v141
	v_rcp_f32_e32 v142, v142
	v_rcp_f32_e32 v143, v143
	v_rcp_f32_e32 v144, v144
	v_rcp_f32_e32 v145, v145
	v_rcp_f32_e32 v146, v146
	v_rcp_f32_e32 v147, v147
	v_mul_f32_e32 v140, v16, v140
	v_mul_f32_e32 v141, v17, v141
	v_mul_f32_e32 v142, v18, v142
	v_mul_f32_e32 v143, v19, v143
	v_mul_f32_e32 v144, v20, v144
	v_mul_f32_e32 v145, v21, v145
	v_mul_f32_e32 v146, v22, v146
	v_mul_f32_e32 v147, v23, v147
	v_mul_f32_e32 v140, v0, v140
	v_mul_f32_e32 v141, v1, v141
	v_mul_f32_e32 v142, v2, v142
	v_mul_f32_e32 v143, v3, v143
	v_mul_f32_e32 v144, v4, v144
	v_mul_f32_e32 v145, v5, v145
	v_mul_f32_e32 v146, v6, v146
	v_mul_f32_e32 v147, v7, v147
	v_cvt_pk_bf16_f32 v156, v140, v141
	v_cvt_pk_bf16_f32 v157, v142, v143
	v_cvt_pk_bf16_f32 v158, v144, v145
	v_cvt_pk_bf16_f32 v159, v146, v147
	global_store_dwordx4 v133, v[156:159], s[12:13] offset:2048 sc0 sc1
	v_mul_f32_e32 v140, 0xbfb8aa3b, v24
	v_mul_f32_e32 v141, 0xbfb8aa3b, v25
	v_mul_f32_e32 v142, 0xbfb8aa3b, v26
	v_mul_f32_e32 v143, 0xbfb8aa3b, v27
	v_mul_f32_e32 v144, 0xbfb8aa3b, v28
	v_mul_f32_e32 v145, 0xbfb8aa3b, v29
	v_mul_f32_e32 v146, 0xbfb8aa3b, v30
	v_mul_f32_e32 v147, 0xbfb8aa3b, v31
	v_exp_f32_e32 v140, v140
	v_exp_f32_e32 v141, v141
	v_exp_f32_e32 v142, v142
	v_exp_f32_e32 v143, v143
	v_exp_f32_e32 v144, v144
	v_exp_f32_e32 v145, v145
	v_exp_f32_e32 v146, v146
	v_exp_f32_e32 v147, v147
	v_add_f32_e32 v140, 1.0, v140
	v_add_f32_e32 v141, 1.0, v141
	v_add_f32_e32 v142, 1.0, v142
	v_add_f32_e32 v143, 1.0, v143
	v_add_f32_e32 v144, 1.0, v144
	v_add_f32_e32 v145, 1.0, v145
	v_add_f32_e32 v146, 1.0, v146
	v_add_f32_e32 v147, 1.0, v147
	v_rcp_f32_e32 v140, v140
	v_rcp_f32_e32 v141, v141
	v_rcp_f32_e32 v142, v142
	v_rcp_f32_e32 v143, v143
	v_rcp_f32_e32 v144, v144
	v_rcp_f32_e32 v145, v145
	v_rcp_f32_e32 v146, v146
	v_rcp_f32_e32 v147, v147
	v_mul_f32_e32 v140, v24, v140
	v_mul_f32_e32 v141, v25, v141
	v_mul_f32_e32 v142, v26, v142
	v_mul_f32_e32 v143, v27, v143
	v_mul_f32_e32 v144, v28, v144
	v_mul_f32_e32 v145, v29, v145
	v_mul_f32_e32 v146, v30, v146
	v_mul_f32_e32 v147, v31, v147
	v_mul_f32_e32 v140, v8, v140
	v_mul_f32_e32 v141, v9, v141
	v_mul_f32_e32 v142, v10, v142
	v_mul_f32_e32 v143, v11, v143
	v_mul_f32_e32 v144, v12, v144
	v_mul_f32_e32 v145, v13, v145
	v_mul_f32_e32 v146, v14, v146
	v_mul_f32_e32 v147, v15, v147
	v_cvt_pk_bf16_f32 v160, v140, v141
	v_cvt_pk_bf16_f32 v161, v142, v143
	v_cvt_pk_bf16_f32 v162, v144, v145
	v_cvt_pk_bf16_f32 v163, v146, v147
	global_store_dwordx4 v133, v[160:163], s[12:13] offset:2304 sc0 sc1
	v_readlane_b32 s0, v254, 11
	s_add_i32 s2, s2, s0
	s_cmp_lt_i32 s2, s3
	s_barrier
	s_cbranch_scc1 .LBB0_1031
